# dil_attn: wave-uniform fast path for interior query blocks (K/V tile addresses from one base + constants, no per-tile range selects)
# baseline (speedup 1.0000x reference)
.LBB0_112:
	v_lshlrev_b32_e32 v0, s46, v194
	v_add3_u32 v191, v193, s33, v0
	v_lshrrev_b32_e32 v0, 1, v191
	v_and_b32_e32 v0, 0x7ffff0, v0
	v_or_b32_e32 v0, s41, v0
	v_add_u32_e32 v244, v193, v111
	v_lshl_or_b32 v176, v0, 9, v189
	v_subrev_u32_e32 v192, 64, v191
	v_lshl_add_u64 v[4:5], v[176:177], 1, s[38:39]
	v_add_u32_e32 v245, v192, v112
	v_add_u32_e32 v246, v191, v103
	global_load_dwordx4 v[228:231], v[4:5], off sc0 sc1
	global_load_dwordx4 v[232:235], v[4:5], off offset:1024 sc0 sc1
	global_load_dwordx4 v[236:239], v[4:5], off offset:2048 sc0 sc1
	global_load_dwordx4 v[240:243], v[4:5], off offset:3072 sc0 sc1
	s_movk_i32 s18, 0x1f0
	v_readfirstlane_b32 s20, v193
	s_sub_i32 s22, s45, 159
	s_nop 1
	s_add_i32 s21, s20, -64
	s_cmp_lt_u32 s21, s22
	s_cbranch_scc0 .Ldil_slowK
	s_mov_b32 s34, 1
	v_lshrrev_b32_e32 v7, 1, v245
	v_and_b32_e32 v7, 0x7ffff0, v7
	v_lshlrev_b32_e32 v6, 4, v245
	v_or_b32_e32 v7, s41, v7
	v_and_or_b32 v6, v6, s18, v113
	v_lshl_add_u32 v176, v7, 9, v6
	v_lshl_add_u64 v[4:5], v[176:177], 1, s[38:39]
	s_mov_b32 s23, 0
	global_load_dwordx4 v[118:121], v[4:5], off sc0 sc1
	global_load_dwordx4 v[122:125], v[4:5], off offset:1024 sc0 sc1
	global_load_dwordx4 v[126:129], v[4:5], off offset:2048 sc0 sc1
	global_load_dwordx4 v[130:133], v[4:5], off offset:3072 sc0 sc1
	s_mov_b32 s22, 16384
	v_lshl_add_u64 v[8:9], v[4:5], 0, s[22:23]
	global_load_dwordx4 v[134:137], v[8:9], off sc0 sc1
	global_load_dwordx4 v[138:141], v[8:9], off offset:1024 sc0 sc1
	global_load_dwordx4 v[142:145], v[8:9], off offset:2048 sc0 sc1
	global_load_dwordx4 v[146:149], v[8:9], off offset:3072 sc0 sc1
	s_mov_b32 s22, 32768
	v_lshl_add_u64 v[8:9], v[4:5], 0, s[22:23]
	global_load_dwordx4 v[150:153], v[8:9], off sc0 sc1
	global_load_dwordx4 v[154:157], v[8:9], off offset:1024 sc0 sc1
	global_load_dwordx4 v[158:161], v[8:9], off offset:2048 sc0 sc1
	global_load_dwordx4 v[162:165], v[8:9], off offset:3072 sc0 sc1
	s_mov_b32 s22, 49152
	v_lshl_add_u64 v[8:9], v[4:5], 0, s[22:23]
	global_load_dwordx4 v[166:169], v[8:9], off sc0 sc1
	global_load_dwordx4 v[170:173], v[8:9], off offset:1024 sc0 sc1
	global_load_dwordx4 v[180:183], v[8:9], off offset:2048 sc0 sc1
	global_load_dwordx4 v[184:187], v[8:9], off offset:3072 sc0 sc1
	s_mov_b32 s22, 65536
	v_lshl_add_u64 v[8:9], v[4:5], 0, s[22:23]
	global_load_dwordx4 v[196:199], v[8:9], off sc0 sc1
	global_load_dwordx4 v[214:217], v[8:9], off offset:1024 sc0 sc1
	global_load_dwordx4 v[218:221], v[8:9], off offset:2048 sc0 sc1
	global_load_dwordx4 v[222:225], v[8:9], off offset:3072 sc0 sc1
	v_add_u32_e32 v192, v192, v100
	s_movk_i32 s20, 0xe000
	v_lshlrev_b32_e32 v7, 8, v192
	v_and_b32_e32 v6, 31, v192
	v_and_or_b32 v6, v7, s20, v6
	v_or_b32_e32 v176, v6, v190
	v_lshl_add_u64 v[174:175], v[176:177], 1, s[2:3]
	global_load_dwordx4 v[88:91], v[174:175], off sc0 sc1
	global_load_dwordx4 v[92:95], v[174:175], off offset:2048 sc0 sc1
	global_load_dwordx4 v[80:83], v[174:175], off offset:32 sc0 sc1
	global_load_dwordx4 v[84:87], v[174:175], off offset:2080 sc0 sc1
	s_mov_b64 s[16:17], -1
	s_mov_b64 vcc, -1
	s_branch .Ldil_Kdone
.Ldil_slowK:
	s_mov_b32 s34, 0
	v_cmp_lt_i32_e32 vcc, -1, v244
	v_cmp_gt_i32_e64 s[16:17], s45, v244
	s_and_b64 vcc, vcc, s[16:17]
	v_cndmask_b32_e32 v6, v246, v245, vcc
	v_lshrrev_b32_e32 v7, 1, v6
	v_and_b32_e32 v7, 0x7ffff0, v7
	v_lshlrev_b32_e32 v6, 4, v6
	v_or_b32_e32 v7, s41, v7
	v_and_or_b32 v6, v6, s18, v113
	v_lshl_add_u32 v176, v7, 9, v6
	v_lshl_add_u64 v[4:5], v[176:177], 1, s[38:39]
	global_load_dwordx4 v[118:121], v[4:5], off sc0 sc1
	global_load_dwordx4 v[122:125], v[4:5], off offset:1024 sc0 sc1
	global_load_dwordx4 v[126:129], v[4:5], off offset:2048 sc0 sc1
	global_load_dwordx4 v[130:133], v[4:5], off offset:3072 sc0 sc1
	v_add_u32_e32 v6, 32, v244
	v_cmp_lt_i32_e32 vcc, -1, v6
	v_cmp_gt_i32_e64 s[16:17], s45, v6
	v_add_u32_e32 v7, 32, v245
	s_and_b64 vcc, vcc, s[16:17]
	v_cndmask_b32_e32 v6, v246, v7, vcc
	v_lshrrev_b32_e32 v7, 1, v6
	v_and_b32_e32 v7, 0x7ffff0, v7
	v_lshlrev_b32_e32 v6, 4, v6
	v_or_b32_e32 v7, s41, v7
	v_and_or_b32 v6, v6, s18, v113
	v_lshl_add_u32 v176, v7, 9, v6
	v_lshl_add_u64 v[4:5], v[176:177], 1, s[38:39]
	global_load_dwordx4 v[134:137], v[4:5], off sc0 sc1
	global_load_dwordx4 v[138:141], v[4:5], off offset:1024 sc0 sc1
	global_load_dwordx4 v[142:145], v[4:5], off offset:2048 sc0 sc1
	global_load_dwordx4 v[146:149], v[4:5], off offset:3072 sc0 sc1
	v_add_u32_e32 v6, 64, v244
	v_cmp_lt_i32_e32 vcc, -1, v6
	v_cmp_gt_i32_e64 s[16:17], s45, v6
	v_add_u32_e32 v7, 64, v245
	s_and_b64 vcc, vcc, s[16:17]
	v_cndmask_b32_e32 v6, v246, v7, vcc
	v_lshrrev_b32_e32 v7, 1, v6
	v_and_b32_e32 v7, 0x7ffff0, v7
	v_lshlrev_b32_e32 v6, 4, v6
	v_or_b32_e32 v7, s41, v7
	v_and_or_b32 v6, v6, s18, v113
	v_lshl_add_u32 v176, v7, 9, v6
	v_lshl_add_u64 v[4:5], v[176:177], 1, s[38:39]
	global_load_dwordx4 v[150:153], v[4:5], off sc0 sc1
	global_load_dwordx4 v[154:157], v[4:5], off offset:1024 sc0 sc1
	global_load_dwordx4 v[158:161], v[4:5], off offset:2048 sc0 sc1
	global_load_dwordx4 v[162:165], v[4:5], off offset:3072 sc0 sc1
	v_add_u32_e32 v6, 96, v244
	v_cmp_lt_i32_e32 vcc, -1, v6
	v_cmp_gt_i32_e64 s[16:17], s45, v6
	v_add_u32_e32 v7, 96, v245
	s_and_b64 vcc, vcc, s[16:17]
	v_cndmask_b32_e32 v6, v246, v7, vcc
	v_lshrrev_b32_e32 v7, 1, v6
	v_and_b32_e32 v7, 0x7ffff0, v7
	v_lshlrev_b32_e32 v6, 4, v6
	v_or_b32_e32 v7, s41, v7
	v_and_or_b32 v6, v6, s18, v113
	v_lshl_add_u32 v176, v7, 9, v6
	v_lshl_add_u64 v[4:5], v[176:177], 1, s[38:39]
	global_load_dwordx4 v[166:169], v[4:5], off sc0 sc1
	global_load_dwordx4 v[170:173], v[4:5], off offset:1024 sc0 sc1
	global_load_dwordx4 v[180:183], v[4:5], off offset:2048 sc0 sc1
	global_load_dwordx4 v[184:187], v[4:5], off offset:3072 sc0 sc1
	v_add_u32_e32 v6, 128, v244
	v_cmp_lt_i32_e32 vcc, -1, v6
	v_cmp_gt_i32_e64 s[16:17], s45, v6
	v_add_u32_e32 v7, 128, v245
	s_and_b64 vcc, vcc, s[16:17]
	v_cndmask_b32_e32 v6, v246, v7, vcc
	v_lshrrev_b32_e32 v7, 1, v6
	v_and_b32_e32 v7, 0x7ffff0, v7
	v_lshlrev_b32_e32 v6, 4, v6
	v_or_b32_e32 v7, s41, v7
	v_and_or_b32 v6, v6, s18, v113
	v_lshl_add_u32 v176, v7, 9, v6
	v_lshl_add_u64 v[4:5], v[176:177], 1, s[38:39]
	global_load_dwordx4 v[196:199], v[4:5], off sc0 sc1
	global_load_dwordx4 v[214:217], v[4:5], off offset:1024 sc0 sc1
	global_load_dwordx4 v[218:221], v[4:5], off offset:2048 sc0 sc1
	global_load_dwordx4 v[222:225], v[4:5], off offset:3072 sc0 sc1
	v_add_u32_e32 v192, v192, v100
	v_cmp_lt_i32_e32 vcc, 63, v193
	v_cmp_gt_i32_e64 s[16:17], s47, v193
	s_and_b64 s[16:17], vcc, s[16:17]
	v_cmp_lt_i32_e32 vcc, 47, v193
	v_cmp_gt_i32_e64 s[18:19], s48, v193
	s_and_b64 vcc, vcc, s[18:19]
	s_movk_i32 s20, 0xe000
	v_cndmask_b32_e64 v6, v191, v192, s[16:17]
	v_add_u32_e32 v8, 16, v192
	v_lshlrev_b32_e32 v7, 8, v6
	v_and_b32_e32 v6, 31, v6
	v_cndmask_b32_e32 v8, v191, v8, vcc
	v_and_or_b32 v6, v7, s20, v6
	v_or_b32_e32 v176, v6, v190
	v_lshl_add_u64 v[4:5], v[176:177], 1, s[2:3]
	global_load_dwordx4 v[88:91], v[4:5], off sc0 sc1
	global_load_dwordx4 v[92:95], v[4:5], off offset:2048 sc0 sc1
	v_lshlrev_b32_e32 v7, 8, v8
	v_and_b32_e32 v8, 31, v8
	v_and_or_b32 v8, v7, s20, v8
	v_or_b32_e32 v176, v8, v190
	v_lshl_add_u64 v[4:5], v[176:177], 1, s[2:3]
	global_load_dwordx4 v[80:83], v[4:5], off sc0 sc1
	global_load_dwordx4 v[84:87], v[4:5], off offset:2048 sc0 sc1
.Ldil_Kdone:
	v_readlane_b32 s18, v249, 26
	v_readlane_b32 s19, v249, 27
	s_waitcnt vmcnt(20)
	v_mfma_f32_32x32x16_bf16 v[64:79], v[118:121], v[228:231], 0
	v_mfma_f32_32x32x16_bf16 v[64:79], v[122:125], v[232:235], v[64:79]
	v_mfma_f32_32x32x16_bf16 v[64:79], v[126:129], v[236:239], v[64:79]
	v_mfma_f32_32x32x16_bf16 v[64:79], v[130:133], v[240:243], v[64:79]
	s_waitcnt vmcnt(16)
	v_mfma_f32_32x32x16_bf16 v[48:63], v[134:137], v[228:231], 0
	v_mfma_f32_32x32x16_bf16 v[48:63], v[138:141], v[232:235], v[48:63]
	v_mfma_f32_32x32x16_bf16 v[48:63], v[142:145], v[236:239], v[48:63]
	v_mfma_f32_32x32x16_bf16 v[48:63], v[146:149], v[240:243], v[48:63]
	s_waitcnt vmcnt(12)
	v_mfma_f32_32x32x16_bf16 v[32:47], v[150:153], v[228:231], 0
	v_mfma_f32_32x32x16_bf16 v[32:47], v[154:157], v[232:235], v[32:47]
	v_mfma_f32_32x32x16_bf16 v[32:47], v[158:161], v[236:239], v[32:47]
	v_mfma_f32_32x32x16_bf16 v[32:47], v[162:165], v[240:243], v[32:47]
	s_waitcnt vmcnt(8)
	v_mfma_f32_32x32x16_bf16 v[16:31], v[166:169], v[228:231], 0
	v_mfma_f32_32x32x16_bf16 v[16:31], v[170:173], v[232:235], v[16:31]
	v_mfma_f32_32x32x16_bf16 v[16:31], v[180:183], v[236:239], v[16:31]
	v_mfma_f32_32x32x16_bf16 v[16:31], v[184:187], v[240:243], v[16:31]
	s_waitcnt vmcnt(4)
	v_mfma_f32_32x32x16_bf16 v[0:15], v[196:199], v[228:231], 0
	v_mfma_f32_32x32x16_bf16 v[0:15], v[214:217], v[232:235], v[0:15]
	v_mfma_f32_32x32x16_bf16 v[0:15], v[218:221], v[236:239], v[0:15]
	v_mfma_f32_32x32x16_bf16 v[0:15], v[222:225], v[240:243], v[0:15]
	s_cmp_eq_u32 s34, 0
	s_cbranch_scc1 .Ldil_slowV
	s_mov_b32 s23, 0
	s_mov_b32 s22, 16384
	v_lshl_add_u64 v[238:239], v[174:175], 0, s[22:23]
	global_load_dwordx4 v[118:121], v[238:239], off sc0 sc1
	global_load_dwordx4 v[122:125], v[238:239], off offset:2048 sc0 sc1
	global_load_dwordx4 v[126:129], v[238:239], off offset:32 sc0 sc1
	global_load_dwordx4 v[130:133], v[238:239], off offset:2080 sc0 sc1
	s_mov_b32 s22, 32768
	v_lshl_add_u64 v[238:239], v[174:175], 0, s[22:23]
	global_load_dwordx4 v[134:137], v[238:239], off sc0 sc1
	global_load_dwordx4 v[138:141], v[238:239], off offset:2048 sc0 sc1
	global_load_dwordx4 v[142:145], v[238:239], off offset:32 sc0 sc1
	global_load_dwordx4 v[146:149], v[238:239], off offset:2080 sc0 sc1
	s_mov_b32 s22, 49152
	v_lshl_add_u64 v[238:239], v[174:175], 0, s[22:23]
	global_load_dwordx4 v[150:153], v[238:239], off sc0 sc1
	global_load_dwordx4 v[154:157], v[238:239], off offset:2048 sc0 sc1
	global_load_dwordx4 v[158:161], v[238:239], off offset:32 sc0 sc1
	global_load_dwordx4 v[162:165], v[238:239], off offset:2080 sc0 sc1
	s_mov_b32 s22, 65536
	v_lshl_add_u64 v[238:239], v[174:175], 0, s[22:23]
	global_load_dwordx4 v[166:169], v[238:239], off sc0 sc1
	global_load_dwordx4 v[170:173], v[238:239], off offset:2048 sc0 sc1
	global_load_dwordx4 v[180:183], v[238:239], off offset:32 sc0 sc1
	global_load_dwordx4 v[184:187], v[238:239], off offset:2080 sc0 sc1
	s_branch .Ldil_Vdone
.Ldil_slowV:
	s_movk_i32 s24, 0xe000
	v_cmp_lt_i32_e64 s[20:21], 31, v193
	v_cmp_gt_i32_e64 s[22:23], s49, v193
	v_add_u32_e32 v188, 32, v192
	s_and_b64 s[20:21], s[20:21], s[22:23]
	v_cndmask_b32_e64 v188, v191, v188, s[20:21]
	v_lshlrev_b32_e32 v239, 8, v188
	v_and_b32_e32 v188, 31, v188
	v_and_or_b32 v188, v239, s24, v188
	v_or_b32_e32 v176, v188, v190
	v_lshl_add_u64 v[174:175], v[176:177], 1, s[2:3]
	global_load_dwordx4 v[118:121], v[174:175], off sc0 sc1
	global_load_dwordx4 v[122:125], v[174:175], off offset:2048 sc0 sc1
	v_cmp_lt_i32_e64 s[20:21], 15, v193
	v_cmp_gt_i32_e64 s[22:23], s50, v193
	v_add_u32_e32 v188, 48, v192
	s_and_b64 s[20:21], s[20:21], s[22:23]
	v_cndmask_b32_e64 v188, v191, v188, s[20:21]
	v_lshlrev_b32_e32 v239, 8, v188
	v_and_b32_e32 v188, 31, v188
	v_and_or_b32 v188, v239, s24, v188
	v_or_b32_e32 v176, v188, v190
	v_lshl_add_u64 v[174:175], v[176:177], 1, s[2:3]
	global_load_dwordx4 v[126:129], v[174:175], off sc0 sc1
	global_load_dwordx4 v[130:133], v[174:175], off offset:2048 sc0 sc1
	v_cmp_lt_i32_e64 s[20:21], -1, v193
	v_cmp_gt_i32_e64 s[22:23], s45, v193
	v_add_u32_e32 v188, 64, v192
	s_and_b64 s[20:21], s[20:21], s[22:23]
	v_cndmask_b32_e64 v188, v191, v188, s[20:21]
	v_lshlrev_b32_e32 v239, 8, v188
	v_and_b32_e32 v188, 31, v188
	v_and_or_b32 v188, v239, s24, v188
	v_or_b32_e32 v176, v188, v190
	v_lshl_add_u64 v[174:175], v[176:177], 1, s[2:3]
	global_load_dwordx4 v[134:137], v[174:175], off sc0 sc1
	global_load_dwordx4 v[138:141], v[174:175], off offset:2048 sc0 sc1
	s_movk_i32 s25, 0xffef
	v_cmp_lt_i32_e64 s[20:21], s25, v193
	v_cmp_gt_i32_e64 s[22:23], s51, v193
	v_add_u32_e32 v188, 80, v192
	s_and_b64 s[20:21], s[20:21], s[22:23]
	v_cndmask_b32_e64 v188, v191, v188, s[20:21]
	v_lshlrev_b32_e32 v239, 8, v188
	v_and_b32_e32 v188, 31, v188
	v_and_or_b32 v188, v239, s24, v188
	v_or_b32_e32 v176, v188, v190
	v_lshl_add_u64 v[174:175], v[176:177], 1, s[2:3]
	global_load_dwordx4 v[142:145], v[174:175], off sc0 sc1
	global_load_dwordx4 v[146:149], v[174:175], off offset:2048 sc0 sc1
	s_movk_i32 s25, 0xffdf
	v_cmp_lt_i32_e64 s[20:21], s25, v193
	v_cmp_gt_i32_e64 s[22:23], s52, v193
	v_add_u32_e32 v188, 96, v192
	s_and_b64 s[20:21], s[20:21], s[22:23]
	v_cndmask_b32_e64 v188, v191, v188, s[20:21]
	v_lshlrev_b32_e32 v239, 8, v188
	v_and_b32_e32 v188, 31, v188
	v_and_or_b32 v188, v239, s24, v188
	v_or_b32_e32 v176, v188, v190
	v_lshl_add_u64 v[174:175], v[176:177], 1, s[2:3]
	global_load_dwordx4 v[150:153], v[174:175], off sc0 sc1
	global_load_dwordx4 v[154:157], v[174:175], off offset:2048 sc0 sc1
	s_movk_i32 s25, 0xffcf
	v_cmp_lt_i32_e64 s[20:21], s25, v193
	v_cmp_gt_i32_e64 s[22:23], s53, v193
	v_add_u32_e32 v188, 112, v192
	s_and_b64 s[20:21], s[20:21], s[22:23]
	v_cndmask_b32_e64 v188, v191, v188, s[20:21]
	v_lshlrev_b32_e32 v239, 8, v188
	v_and_b32_e32 v188, 31, v188
	v_and_or_b32 v188, v239, s24, v188
	v_or_b32_e32 v176, v188, v190
	v_lshl_add_u64 v[174:175], v[176:177], 1, s[2:3]
	global_load_dwordx4 v[158:161], v[174:175], off sc0 sc1
	global_load_dwordx4 v[162:165], v[174:175], off offset:2048 sc0 sc1
	s_movk_i32 s25, 0xffbf
	v_cmp_lt_i32_e64 s[20:21], s25, v193
	v_cmp_gt_i32_e64 s[22:23], s54, v193
	v_add_u32_e32 v188, 128, v192
	s_and_b64 s[20:21], s[20:21], s[22:23]
	v_cndmask_b32_e64 v188, v191, v188, s[20:21]
	v_lshlrev_b32_e32 v239, 8, v188
	v_and_b32_e32 v188, 31, v188
	v_and_or_b32 v188, v239, s24, v188
	v_or_b32_e32 v176, v188, v190
	v_lshl_add_u64 v[174:175], v[176:177], 1, s[2:3]
	global_load_dwordx4 v[166:169], v[174:175], off sc0 sc1
	global_load_dwordx4 v[170:173], v[174:175], off offset:2048 sc0 sc1
	s_movk_i32 s25, 0xffaf
	v_cmp_lt_i32_e64 s[20:21], s25, v193
	v_cmp_gt_i32_e64 s[22:23], s55, v193
	v_add_u32_e32 v188, 144, v192
	s_and_b64 s[20:21], s[20:21], s[22:23]
	v_cndmask_b32_e64 v188, v191, v188, s[20:21]
	v_lshlrev_b32_e32 v239, 8, v188
	v_and_b32_e32 v188, 31, v188
	v_and_or_b32 v188, v239, s24, v188
	v_or_b32_e32 v176, v188, v190
	v_lshl_add_u64 v[174:175], v[176:177], 1, s[2:3]
	global_load_dwordx4 v[180:183], v[174:175], off sc0 sc1
	global_load_dwordx4 v[184:187], v[174:175], off offset:2048 sc0 sc1
.Ldil_Vdone:
	v_mov_b32_e32 v254, 0xf149f2ca
	ds_read_b32 v213, v117 offset:640
	ds_read_b32 v214, v117 offset:644
	ds_read_b32 v215, v117 offset:648
	ds_read_b32 v216, v117 offset:652
	ds_read_b32 v217, v117 offset:656
	ds_read_b32 v218, v117 offset:660
	ds_read_b32 v219, v117 offset:664
	ds_read_b32 v220, v117 offset:668
	ds_read_b32 v221, v117 offset:704
	ds_read_b32 v222, v117 offset:708
	ds_read_b32 v223, v117 offset:712
	ds_read_b32 v224, v117 offset:716
	ds_read_b32 v225, v117 offset:720
	ds_read_b32 v226, v117 offset:724
	ds_read_b32 v227, v117 offset:728
	s_and_b64 s[20:21], s[16:17], s[18:19]
	s_waitcnt lgkmcnt(10)
	v_add_f32_e32 v213, v64, v213
	v_cndmask_b32_e64 v97, v254, v213, s[20:21]
	v_readlane_b32 s18, v249, 21
	v_readlane_b32 s19, v249, 22
	s_and_b64 s[20:21], s[16:17], s[18:19]
	v_add_f32_e32 v214, v65, v214
	v_cndmask_b32_e64 v96, v254, v214, s[20:21]
	v_readlane_b32 s18, v249, 18
	v_readlane_b32 s19, v249, 19
	s_and_b64 s[20:21], s[16:17], s[18:19]
	v_add_f32_e32 v215, v66, v215
	v_cndmask_b32_e64 v65, v254, v215, s[20:21]
	v_readlane_b32 s18, v249, 30
	v_readlane_b32 s19, v249, 31
	s_and_b64 s[20:21], s[16:17], s[18:19]
	v_add_f32_e32 v216, v67, v216
	v_cndmask_b32_e64 v64, v254, v216, s[20:21]
	v_readlane_b32 s18, v249, 38
	v_readlane_b32 s19, v249, 39
	s_and_b64 s[20:21], s[16:17], s[18:19]
	v_add_f32_e32 v217, v68, v217
	v_cndmask_b32_e64 v67, v254, v217, s[20:21]
	ds_read_b32 v213, v117 offset:732
	ds_read_b32 v214, v117 offset:768
	ds_read_b32 v215, v117 offset:772
	ds_read_b32 v216, v117 offset:776
	ds_read_b32 v217, v117 offset:780
	v_readlane_b32 s18, v249, 33
	v_readlane_b32 s19, v249, 34
	s_and_b64 s[20:21], s[16:17], s[18:19]
	s_waitcnt lgkmcnt(10)
	v_add_f32_e32 v218, v69, v218
	v_cndmask_b32_e64 v66, v254, v218, s[20:21]
	s_and_b64 s[20:21], s[16:17], s[56:57]
	v_add_f32_e32 v219, v70, v219
	v_cndmask_b32_e64 v69, v254, v219, s[20:21]
	s_and_b64 s[18:19], s[16:17], s[58:59]
	v_add_f32_e32 v220, v71, v220
	v_cndmask_b32_e64 v68, v254, v220, s[18:19]
	s_and_b64 s[18:19], vcc, s[60:61]
	v_add_f32_e32 v221, v72, v221
	v_cndmask_b32_e64 v71, v254, v221, s[18:19]
	s_and_b64 s[18:19], vcc, s[62:63]
	v_add_f32_e32 v222, v73, v222
	v_cndmask_b32_e64 v70, v254, v222, s[18:19]
	ds_read_b32 v218, v117 offset:784
	ds_read_b32 v219, v117 offset:788
	ds_read_b32 v220, v117 offset:792
	ds_read_b32 v221, v117 offset:796
	ds_read_b32 v222, v117 offset:832
	s_and_b64 s[18:19], vcc, s[64:65]
	s_waitcnt lgkmcnt(10)
	v_add_f32_e32 v223, v74, v223
	v_cndmask_b32_e64 v73, v254, v223, s[18:19]
	s_and_b64 s[18:19], vcc, s[66:67]
	v_add_f32_e32 v224, v75, v224
	v_cndmask_b32_e64 v72, v254, v224, s[18:19]
	s_and_b64 s[18:19], vcc, s[68:69]
	v_add_f32_e32 v225, v76, v225
	v_cndmask_b32_e64 v75, v254, v225, s[18:19]
	s_and_b64 s[18:19], vcc, s[70:71]
	v_add_f32_e32 v226, v77, v226
	v_cndmask_b32_e64 v74, v254, v226, s[18:19]
	s_and_b64 s[18:19], vcc, s[72:73]
	v_add_f32_e32 v227, v78, v227
	v_cndmask_b32_e64 v77, v254, v227, s[18:19]
	ds_read_b32 v223, v117 offset:836
	ds_read_b32 v224, v117 offset:840
	ds_read_b32 v225, v117 offset:844
	ds_read_b32 v226, v117 offset:848
	ds_read_b32 v227, v117 offset:852
	s_and_b64 s[18:19], vcc, s[74:75]
	s_waitcnt lgkmcnt(10)
	v_add_f32_e32 v213, v79, v213
	v_cndmask_b32_e64 v76, v254, v213, s[18:19]
	v_cmp_lt_i32_e32 vcc, 31, v193
	v_cmp_gt_i32_e64 s[16:17], s49, v193
	s_and_b64 s[18:19], vcc, s[16:17]
	v_add_f32_e32 v214, v48, v214
	v_cndmask_b32_e64 v79, v254, v214, s[18:19]
	v_add_f32_e32 v215, v49, v215
	v_cndmask_b32_e64 v78, v254, v215, s[18:19]
	v_add_f32_e32 v216, v50, v216
	v_cndmask_b32_e64 v49, v254, v216, s[18:19]
	v_add_f32_e32 v217, v51, v217
	v_cndmask_b32_e64 v48, v254, v217, s[18:19]
	ds_read_b32 v213, v117 offset:856
	ds_read_b32 v214, v117 offset:860
	ds_read_b32 v215, v117 offset:896
	ds_read_b32 v216, v117 offset:900
	ds_read_b32 v217, v117 offset:904
	s_waitcnt lgkmcnt(10)
	v_add_f32_e32 v218, v52, v218
	v_cndmask_b32_e64 v51, v254, v218, s[18:19]
	v_add_f32_e32 v219, v53, v219
	v_cndmask_b32_e64 v50, v254, v219, s[18:19]
	v_add_f32_e32 v220, v54, v220
	v_cndmask_b32_e64 v53, v254, v220, s[18:19]
	v_add_f32_e32 v221, v55, v221
	v_cndmask_b32_e64 v52, v254, v221, s[18:19]
	v_cmp_lt_i32_e32 vcc, 15, v193
	v_cmp_gt_i32_e64 s[16:17], s50, v193
	s_and_b64 s[28:29], vcc, s[16:17]
	v_add_f32_e32 v222, v56, v222
	v_cndmask_b32_e64 v55, v254, v222, s[28:29]
	ds_read_b32 v218, v117 offset:908
	ds_read_b32 v219, v117 offset:912
	ds_read_b32 v220, v117 offset:916
	ds_read_b32 v221, v117 offset:920
	ds_read_b32 v222, v117 offset:924
	s_waitcnt lgkmcnt(10)
	v_add_f32_e32 v223, v57, v223
	v_cndmask_b32_e64 v54, v254, v223, s[28:29]
	v_add_f32_e32 v224, v58, v224
	v_cndmask_b32_e64 v57, v254, v224, s[28:29]
	v_add_f32_e32 v225, v59, v225
	v_cndmask_b32_e64 v56, v254, v225, s[28:29]
	v_add_f32_e32 v226, v60, v226
	v_cndmask_b32_e64 v59, v254, v226, s[28:29]
	v_add_f32_e32 v227, v61, v227
	v_cndmask_b32_e64 v58, v254, v227, s[28:29]
	ds_read_b32 v223, v117 offset:960
	ds_read_b32 v224, v117 offset:964
	ds_read_b32 v225, v117 offset:968
	ds_read_b32 v226, v117 offset:972
	ds_read_b32 v227, v117 offset:976
	s_waitcnt lgkmcnt(10)
	v_add_f32_e32 v213, v62, v213
	v_cndmask_b32_e64 v61, v254, v213, s[28:29]
	v_add_f32_e32 v214, v63, v214
	v_cndmask_b32_e64 v60, v254, v214, s[28:29]
	v_cmp_lt_i32_e32 vcc, -1, v193
	v_cmp_gt_i32_e64 s[16:17], s45, v193
	s_and_b64 s[22:23], vcc, s[16:17]
	v_add_f32_e32 v215, v32, v215
	v_cndmask_b32_e64 v63, v254, v215, s[22:23]
	v_add_f32_e32 v216, v33, v216
	v_cndmask_b32_e64 v62, v254, v216, s[22:23]
	v_add_f32_e32 v217, v34, v217
	v_cndmask_b32_e64 v98, v254, v217, s[22:23]
	ds_read_b32 v213, v117 offset:980
	ds_read_b32 v214, v117 offset:984
	ds_read_b32 v215, v117 offset:988
	ds_read_b32 v216, v117 offset:1024
	ds_read_b32 v217, v117 offset:1028
	s_waitcnt lgkmcnt(10)
	v_add_f32_e32 v218, v35, v218
	v_cndmask_b32_e64 v32, v254, v218, s[22:23]
	v_add_f32_e32 v219, v36, v219
	v_cndmask_b32_e64 v176, v254, v219, s[22:23]
	v_add_f32_e32 v220, v37, v220
	v_cndmask_b32_e64 v99, v254, v220, s[22:23]
	v_add_f32_e32 v221, v38, v221
	v_cndmask_b32_e64 v37, v254, v221, s[22:23]
	v_add_f32_e32 v222, v39, v222
	v_cndmask_b32_e64 v36, v254, v222, s[22:23]
	ds_read_b32 v218, v117 offset:1032
	ds_read_b32 v219, v117 offset:1036
	ds_read_b32 v220, v117 offset:1040
	ds_read_b32 v221, v117 offset:1044
	ds_read_b32 v222, v117 offset:1048
	s_movk_i32 s16, 0xffef
	v_cmp_lt_i32_e32 vcc, s16, v193
	v_cmp_gt_i32_e64 s[16:17], s51, v193
	s_and_b64 s[20:21], vcc, s[16:17]
	s_waitcnt lgkmcnt(10)
	v_add_f32_e32 v223, v40, v223
	v_cndmask_b32_e64 v39, v254, v223, s[20:21]
	v_add_f32_e32 v224, v41, v224
	v_cndmask_b32_e64 v38, v254, v224, s[20:21]
	v_add_f32_e32 v225, v42, v225
	v_cndmask_b32_e64 v41, v254, v225, s[20:21]
	v_add_f32_e32 v226, v43, v226
	v_cndmask_b32_e64 v40, v254, v226, s[20:21]
	v_add_f32_e32 v227, v44, v227
	v_cndmask_b32_e64 v43, v254, v227, s[20:21]
	ds_read_b32 v223, v117 offset:1052
	ds_read_b32 v224, v117 offset:1088
	ds_read_b32 v225, v117 offset:1092
	ds_read_b32 v226, v117 offset:1096
	ds_read_b32 v227, v117 offset:1100
	s_waitcnt lgkmcnt(10)
	v_add_f32_e32 v213, v45, v213
	v_cndmask_b32_e64 v42, v254, v213, s[20:21]
	v_add_f32_e32 v214, v46, v214
	v_cndmask_b32_e64 v45, v254, v214, s[20:21]
	v_add_f32_e32 v215, v47, v215
	v_cndmask_b32_e64 v44, v254, v215, s[20:21]
	s_movk_i32 s16, 0xffdf
	v_cmp_lt_i32_e32 vcc, s16, v193
	v_cmp_gt_i32_e64 s[16:17], s52, v193
	s_and_b64 s[16:17], vcc, s[16:17]
	v_add_f32_e32 v216, v16, v216
	v_cndmask_b32_e64 v47, v254, v216, s[16:17]
	v_add_f32_e32 v217, v17, v217
	v_cndmask_b32_e64 v46, v254, v217, s[16:17]
	ds_read_b32 v213, v117 offset:1104
	ds_read_b32 v214, v117 offset:1108
	ds_read_b32 v215, v117 offset:1112
	ds_read_b32 v216, v117 offset:1116
	ds_read_b32 v217, v117 offset:1152
	s_waitcnt lgkmcnt(10)
	v_add_f32_e32 v218, v18, v218
	v_cndmask_b32_e64 v17, v254, v218, s[16:17]
	v_add_f32_e32 v219, v19, v219
	v_cndmask_b32_e64 v16, v254, v219, s[16:17]
	v_add_f32_e32 v220, v20, v220
	v_cndmask_b32_e64 v19, v254, v220, s[16:17]
	v_add_f32_e32 v221, v21, v221
	v_cndmask_b32_e64 v18, v254, v221, s[16:17]
	v_add_f32_e32 v222, v22, v222
	v_cndmask_b32_e64 v21, v254, v222, s[16:17]
	ds_read_b32 v218, v117 offset:1156
	ds_read_b32 v219, v117 offset:1160
	ds_read_b32 v220, v117 offset:1164
	ds_read_b32 v221, v117 offset:1168
	ds_read_b32 v222, v117 offset:1172
	s_waitcnt lgkmcnt(10)
	v_add_f32_e32 v223, v23, v223
	v_cndmask_b32_e64 v20, v254, v223, s[16:17]
	s_movk_i32 s24, 0xffcf
	v_cmp_lt_i32_e32 vcc, s24, v193
	v_cmp_gt_i32_e64 s[24:25], s53, v193
	s_and_b64 s[24:25], vcc, s[24:25]
	v_add_f32_e32 v224, v24, v224
	v_cndmask_b32_e64 v23, v254, v224, s[24:25]
	v_add_f32_e32 v225, v25, v225
	v_cndmask_b32_e64 v22, v254, v225, s[24:25]
	v_add_f32_e32 v226, v26, v226
	v_cndmask_b32_e64 v25, v254, v226, s[24:25]
	v_add_f32_e32 v227, v27, v227
	v_cndmask_b32_e64 v24, v254, v227, s[24:25]
	ds_read_b32 v223, v117 offset:1176
	ds_read_b32 v224, v117 offset:1180
	ds_read_b32 v225, v117 offset:1216
	ds_read_b32 v226, v117 offset:1220
	ds_read_b32 v227, v117 offset:1224
	s_waitcnt lgkmcnt(10)
	v_add_f32_e32 v213, v28, v213
	v_cndmask_b32_e64 v27, v254, v213, s[24:25]
	v_add_f32_e32 v214, v29, v214
	v_cndmask_b32_e64 v26, v254, v214, s[24:25]
	v_add_f32_e32 v215, v30, v215
	v_cndmask_b32_e64 v29, v254, v215, s[24:25]
	v_add_f32_e32 v216, v31, v216
	v_cndmask_b32_e64 v28, v254, v216, s[24:25]
	s_movk_i32 s26, 0xffbf
	v_cmp_lt_i32_e32 vcc, s26, v193
	v_cmp_gt_i32_e64 s[26:27], s54, v193
	s_and_b64 s[26:27], vcc, s[26:27]
	s_and_b64 s[34:35], s[26:27], s[76:77]
	v_add_f32_e32 v217, v0, v217
	v_cndmask_b32_e64 v31, v254, v217, s[34:35]
	ds_read_b32 v213, v117 offset:1228
	ds_read_b32 v214, v117 offset:1232
	ds_read_b32 v215, v117 offset:1236
	ds_read_b32 v216, v117 offset:1240
	ds_read_b32 v217, v117 offset:1244
	s_and_b64 s[34:35], s[26:27], s[78:79]
	s_waitcnt lgkmcnt(10)
	v_add_f32_e32 v218, v1, v218
	v_cndmask_b32_e64 v30, v254, v218, s[34:35]
	s_and_b64 s[34:35], s[26:27], s[80:81]
	v_add_f32_e32 v219, v2, v219
	v_cndmask_b32_e64 v235, v254, v219, s[34:35]
	s_and_b64 s[34:35], s[26:27], s[82:83]
	v_add_f32_e32 v220, v3, v220
	v_cndmask_b32_e64 v1, v254, v220, s[34:35]
	s_and_b64 s[34:35], s[26:27], s[84:85]
	v_add_f32_e32 v221, v4, v221
	v_cndmask_b32_e64 v3, v254, v221, s[34:35]
	s_and_b64 s[34:35], s[26:27], s[86:87]
	v_add_f32_e32 v222, v5, v222
	v_cndmask_b32_e64 v2, v254, v222, s[34:35]
	s_and_b64 s[34:35], s[26:27], s[88:89]
	s_waitcnt lgkmcnt(5)
	v_add_f32_e32 v223, v6, v223
	v_cndmask_b32_e64 v5, v254, v223, s[34:35]
	s_and_b64 s[34:35], s[26:27], s[90:91]
	v_add_f32_e32 v224, v7, v224
	v_cndmask_b32_e64 v4, v254, v224, s[34:35]
	s_movk_i32 s30, 0xffaf
	v_cmp_lt_i32_e32 vcc, s30, v193
	v_cmp_gt_i32_e64 s[30:31], s55, v193
	s_and_b64 s[30:31], vcc, s[30:31]
	s_and_b64 vcc, s[30:31], s[92:93]
	v_add_f32_e32 v225, v8, v225
	v_cndmask_b32_e32 v7, v254, v225, vcc
	s_and_b64 vcc, s[30:31], s[94:95]
	v_add_f32_e32 v226, v9, v226
	v_cndmask_b32_e32 v6, v254, v226, vcc
	s_and_b64 vcc, s[30:31], s[96:97]
	v_add_f32_e32 v227, v10, v227
	v_cndmask_b32_e32 v9, v254, v227, vcc
	s_and_b64 vcc, s[30:31], s[4:5]
	s_waitcnt lgkmcnt(0)
	v_add_f32_e32 v213, v11, v213
	v_cndmask_b32_e32 v8, v254, v213, vcc
	s_and_b64 vcc, s[30:31], s[6:7]
	v_add_f32_e32 v214, v12, v214
	v_cndmask_b32_e32 v11, v254, v214, vcc
	s_and_b64 vcc, s[30:31], s[8:9]
	v_add_f32_e32 v215, v13, v215
	v_cndmask_b32_e32 v10, v254, v215, vcc
	s_and_b64 vcc, s[30:31], s[10:11]
	v_add_f32_e32 v216, v14, v216
	v_cndmask_b32_e32 v13, v254, v216, vcc
	s_and_b64 vcc, s[30:31], s[12:13]
	v_add_f32_e32 v217, v15, v217
	v_cndmask_b32_e32 v12, v254, v217, vcc
	v_add_u32_e32 v0, v193, v103
	v_lshl_add_u32 v33, v0, s44, v194
	v_cndmask_b32_e64 v15, 0, 1, s[42:43]
	v_add_u32_e32 v34, s40, v33
	v_mov_b32_e32 v0, 0
	v_mov_b32_e32 v14, 0xf149f2ca
	v_cmp_ne_u32_e64 s[34:35], 1, v15
	s_andn2_b64 vcc, exec, s[42:43]
	v_mov_b32_e32 v233, 0
	s_cbranch_vccnz .LBB0_274
	v_lshl_add_u32 v14, v34, 2, 0
	v_add_u32_e32 v15, 0x22000, v14
	v_add_u32_e32 v35, 0x22800, v14
	ds_read_b32 v14, v15
	ds_read_b32 v233, v35
